# phase 0: co-resident blocks interleave job types (blocks 0..255 transposes then norms, blocks 256..511 norms then transposes)
# speedup vs baseline: 1.0099x; 1.0034x over previous
.LBB0_19:
	s_load_dwordx16 s[76:91], s[0:1], 0x80
	s_load_dwordx4 s[28:31], s[0:1], 0x110
	s_waitcnt lgkmcnt(0)
	s_cmp_gt_i32 s28, 0
	s_cselect_b64 s[4:5], -1, 0
	s_cmp_lt_i32 s29, 1
	s_cselect_b64 s[6:7], -1, 0
	s_or_b64 s[4:5], s[4:5], s[6:7]
	s_and_b64 vcc, exec, s[4:5]
	s_cbranch_vccnz .LBB0_123
	s_cmpk_gt_i32 s2, 0x35e1
	s_cbranch_scc1 .LBB0_78
	s_cmp_ge_u32 s2, 0x100
	s_cbranch_scc1 .Ltr_done
	s_load_dwordx2 s[30:31], s[0:1], 0x40
	s_load_dwordx2 s[32:33], s[0:1], 0xb0
	s_load_dwordx2 s[34:35], s[0:1], 0xc8
	s_load_dwordx2 s[36:37], s[0:1], 0xd0
	s_load_dwordx2 s[38:39], s[0:1], 0xe0
	s_load_dword s3, s[0:1], 0x120
	v_lshrrev_b32_e32 v0, 4, v204
	v_and_b32_e32 v1, 15, v204
	v_lshlrev_b32_e32 v1, 4, v1
	v_lshrrev_b32_e32 v2, 3, v204
	v_and_b32_e32 v3, 7, v204
	v_add_u32_e32 v8, 0, v0
	v_mul_u32_u24_e32 v8, 0x104, v8
	v_add3_u32 v8, v8, v1, 32
	v_add_u32_e32 v72, 0x4100, v8
	v_add_u32_e32 v9, 16, v0
	v_mul_u32_u24_e32 v9, 0x104, v9
	v_add3_u32 v9, v9, v1, 32
	v_add_u32_e32 v73, 0x4100, v9
	v_add_u32_e32 v10, 32, v0
	v_mul_u32_u24_e32 v10, 0x104, v10
	v_add3_u32 v10, v10, v1, 32
	v_add_u32_e32 v74, 0x4100, v10
	v_add_u32_e32 v11, 48, v0
	v_mul_u32_u24_e32 v11, 0x104, v11
	v_add3_u32 v11, v11, v1, 32
	v_add_u32_e32 v75, 0x4100, v11
	v_mul_u32_u24_e32 v12, 0x820, v3
	v_lshl_add_u32 v12, v2, 2, v12
	v_add_u32_e32 v12, 32, v12
	v_add_u32_e32 v13, 0x410, v12
	v_add_u32_e32 v76, 0x4100, v12
	v_add_u32_e32 v77, 0x4100, v13
	v_lshlrev_b32_e32 v14, 12, v2
	v_lshl_add_u32 v14, v3, 4, v14
	v_add_u32_e32 v78, 0, v0
	v_add_u32_e32 v79, 16, v0
	v_add_u32_e32 v80, 32, v0
	v_add_u32_e32 v81, 48, v0
	s_waitcnt lgkmcnt(0)
	s_mov_b32 s4, s2

.LBB0_78:
	s_cmp_lt_u32 s2, 0x100
	s_cbranch_scc1 .Ltz_done
	s_load_dwordx2 s[30:31], s[0:1], 0x40
	s_load_dwordx2 s[32:33], s[0:1], 0xb0
	s_load_dwordx2 s[34:35], s[0:1], 0xc8
	s_load_dwordx2 s[36:37], s[0:1], 0xd0
	s_load_dwordx2 s[38:39], s[0:1], 0xe0
	s_load_dword s3, s[0:1], 0x120
	v_lshrrev_b32_e32 v0, 4, v204
	v_and_b32_e32 v1, 15, v204
	v_lshlrev_b32_e32 v1, 4, v1
	v_lshrrev_b32_e32 v2, 3, v204
	v_and_b32_e32 v3, 7, v204
	v_add_u32_e32 v8, 0, v0
	v_mul_u32_u24_e32 v8, 0x104, v8
	v_add3_u32 v8, v8, v1, 32
	v_add_u32_e32 v72, 0x4100, v8
	v_add_u32_e32 v9, 16, v0
	v_mul_u32_u24_e32 v9, 0x104, v9
	v_add3_u32 v9, v9, v1, 32
	v_add_u32_e32 v73, 0x4100, v9
	v_add_u32_e32 v10, 32, v0
	v_mul_u32_u24_e32 v10, 0x104, v10
	v_add3_u32 v10, v10, v1, 32
	v_add_u32_e32 v74, 0x4100, v10
	v_add_u32_e32 v11, 48, v0
	v_mul_u32_u24_e32 v11, 0x104, v11
	v_add3_u32 v11, v11, v1, 32
	v_add_u32_e32 v75, 0x4100, v11
	v_mul_u32_u24_e32 v12, 0x820, v3
	v_lshl_add_u32 v12, v2, 2, v12
	v_add_u32_e32 v12, 32, v12
	v_add_u32_e32 v13, 0x410, v12
	v_add_u32_e32 v76, 0x4100, v12
	v_add_u32_e32 v77, 0x4100, v13
	v_lshlrev_b32_e32 v14, 12, v2
	v_lshl_add_u32 v14, v3, 4, v14
	v_add_u32_e32 v78, 0, v0
	v_add_u32_e32 v79, 16, v0
	v_add_u32_e32 v80, 32, v0
	v_add_u32_e32 v81, 48, v0
	s_waitcnt lgkmcnt(0)
	s_mov_b32 s4, s2

.Ltz_done:
	s_load_dword s3, s[0:1], 0x120
	s_add_u32 s4, s0, 0x120
	s_addc_u32 s5, s1, 0
	s_waitcnt lgkmcnt(0)
	s_load_dwordx4 s[28:31], s[0:1], 0x110
	v_readlane_b32 s6, v244, 1
	v_readlane_b32 s7, v244, 2
	s_waitcnt lgkmcnt(0)
	s_cmp_lt_i32 s29, 2
	s_cselect_b64 s[4:5], -1, 0
	s_xor_b64 s[6:7], s[6:7], -1
	s_or_b64 s[4:5], s[4:5], s[6:7]
	s_and_b64 vcc, exec, s[4:5]
	s_cbranch_vccnz .LBB0_123
	s_waitcnt vmcnt(0)
	s_barrier
	s_and_saveexec_b64 s[4:5], s[56:57]
	s_cbranch_execz .LBB0_122
	v_readlane_b32 s3, v244, 0
	s_waitcnt vmcnt(0) expcnt(0) lgkmcnt(0)
	s_nop 0
	v_mov_b32_e32 v0, s3
	ds_read_b32 v2, v0
	ds_read_b32 v0, v0 offset:4
	s_waitcnt lgkmcnt(1)
	v_cmp_ne_u32_e32 vcc, 0, v2
	s_cbranch_vccnz .LBB0_93
	s_load_dwordx2 s[10:11], s[0:1], 0x120
	s_load_dword s3, s[0:1], 0x128
	s_add_u32 s6, s58, 0x1000
	s_addc_u32 s7, s59, 0
	s_add_u32 s8, s58, 0x1100
	s_waitcnt lgkmcnt(0)
	s_mul_i32 s9, s11, s10
	s_mul_i32 s3, s9, s3
	s_addc_u32 s9, s59, 0
	s_add_u32 s10, s58, 0x1200
	s_addc_u32 s11, s59, 0
	s_add_u32 s12, s58, 0x1300
	s_addc_u32 s13, s59, 0
	s_mov_b32 s16, 1
	v_mov_b32_e32 v16, 0
	s_branch .LBB0_83
